# grid barrier: workgroups that are not last of their XCD poll the global generation word directly instead of waiting for the per-XCD generation hop
# speedup vs baseline: 1.0056x; 1.0056x over previous
; __device__ __forceinline__ unsigned xb_ld(unsigned* p)              { return __hip_atomic_load(p, __ATOMIC_RELAXED, __HIP_MEMORY_SCOPE_AGENT); }
; __device__ __forceinline__ unsigned xb_add(unsigned* p, unsigned v) { return __hip_atomic_fetch_add(p, v, __ATOMIC_RELAXED, __HIP_MEMORY_SCOPE_AGENT); }
; #define XB_SPIN(cond, bar) do { unsigned _sp = 0; while (cond) { __builtin_amdgcn_s_sleep(1); \
;     if ((++_sp & 255u) == 0u) { if (xb_ld(&(bar)[XB_TMO])) break; if (_sp > XB_SPIN_CAP) { atomicAdd(&(bar)[XB_TMO], 1u); break; } } } } while (0)
; __device__ __forceinline__ void xcd_barrier(const XcdBarrier& b) {
;     ...
;         const unsigned old = xb_add(&bar[XB_XSUB(b.x)], 1u);
;         const unsigned gen = old / nloc;
;         if (old + 1u == (gen + 1u) * nloc) {
;             __builtin_amdgcn_fence(__ATOMIC_RELEASE, "agent");
;             asm volatile("s_waitcnt vmcnt(0)" ::: "memory");
;             const unsigned og = xb_add(&bar[XB_TOP], 1u);
;             const unsigned tg = og / nx;
;             if (og + 1u == (tg + 1u) * nx) xb_add(&bar[XB_TOPGEN], 1u);
;             else XB_SPIN(xb_ld(&bar[XB_TOPGEN]) == tg, bar);
;             __builtin_amdgcn_fence(__ATOMIC_ACQUIRE, "agent");
;             xb_add(&bar[XB_XGEN(b.x)], 1u);
;             asm volatile("s_waitcnt vmcnt(0)" ::: "memory");
;         } else {
;             XB_SPIN(xb_ld(&bar[XB_XGEN(b.x)]) == gen, bar);
.LBB0_59:
	s_lshl_b32 s6, s87, 8
	s_add_u32 s6, s88, s6
	s_addc_u32 s7, s89, 0
	v_mov_b32_e32 v1, 0x1000
	v_mov_b32_e32 v3, 1
	global_atomic_add v3, v1, v3, s[6:7] offset:1024 sc0
	buffer_inv sc1
	v_cvt_f32_u32_e32 v1, v2
	v_sub_u32_e32 v4, 0, v2
	v_rcp_iflag_f32_e32 v1, v1
	s_nop 0
	v_mul_f32_e32 v1, 0x4f7ffffe, v1
	v_cvt_u32_f32_e32 v1, v1
	v_mul_lo_u32 v4, v4, v1
	v_mul_hi_u32 v4, v1, v4
	v_add_u32_e32 v1, v1, v4
	s_waitcnt vmcnt(0)
	v_mul_hi_u32 v1, v3, v1
	v_mul_lo_u32 v4, v1, v2
	v_sub_u32_e32 v4, v3, v4
	v_add_u32_e32 v5, 1, v1
	v_cmp_ge_u32_e32 vcc, v4, v2
	v_add_u32_e32 v3, 1, v3
	s_nop 0
	v_cndmask_b32_e32 v1, v1, v5, vcc
	v_sub_u32_e32 v5, v4, v2
	v_cndmask_b32_e32 v4, v4, v5, vcc
	v_add_u32_e32 v5, 1, v1
	v_cmp_ge_u32_e32 vcc, v4, v2
	s_nop 1
	v_cndmask_b32_e32 v1, v1, v5, vcc
	v_mul_lo_u32 v4, v2, v1
	v_add_u32_e32 v2, v4, v2
	v_cmp_ne_u32_e32 vcc, v3, v2
	s_and_saveexec_b64 s[14:15], vcc
	s_xor_b64 s[14:15], exec, s[14:15]
	s_cbranch_execz .LBB0_73
	s_waitcnt lgkmcnt(0)
	v_mov_b32_e32 v0, 0x3500
	global_load_dword v0, v0, s[88:89] sc1
	s_add_u32 s20, s88, 0x3500
	s_addc_u32 s21, s89, 0
	s_waitcnt vmcnt(0)
	v_cmp_eq_u32_e32 vcc, v0, v1
	s_and_saveexec_b64 s[16:17], vcc
	s_cbranch_execz .LBB0_72
	s_add_u32 s18, s80, 0x10200
	s_addc_u32 s19, s81, 0
	s_mov_b32 s33, 1
	s_mov_b64 s[22:23], 0
	v_mov_b32_e32 v0, 0
	s_branch .LBB0_63

; __device__ __forceinline__ unsigned xb_ld(unsigned* p)              { return __hip_atomic_load(p, __ATOMIC_RELAXED, __HIP_MEMORY_SCOPE_AGENT); }
; __device__ __forceinline__ unsigned xb_add(unsigned* p, unsigned v) { return __hip_atomic_fetch_add(p, v, __ATOMIC_RELAXED, __HIP_MEMORY_SCOPE_AGENT); }
; #define XB_SPIN(cond, bar) do { unsigned _sp = 0; while (cond) { __builtin_amdgcn_s_sleep(1); \
;     if ((++_sp & 255u) == 0u) { if (xb_ld(&(bar)[XB_TMO])) break; if (_sp > XB_SPIN_CAP) { atomicAdd(&(bar)[XB_TMO], 1u); break; } } } } while (0)
; __device__ __forceinline__ void xcd_barrier(const XcdBarrier& b) {
;     ...
;         const unsigned old = xb_add(&bar[XB_XSUB(b.x)], 1u);
;         const unsigned gen = old / nloc;
;         if (old + 1u == (gen + 1u) * nloc) {
;             __builtin_amdgcn_fence(__ATOMIC_RELEASE, "agent");
;             asm volatile("s_waitcnt vmcnt(0)" ::: "memory");
;             const unsigned og = xb_add(&bar[XB_TOP], 1u);
;             const unsigned tg = og / nx;
;             if (og + 1u == (tg + 1u) * nx) xb_add(&bar[XB_TOPGEN], 1u);
;             else XB_SPIN(xb_ld(&bar[XB_TOPGEN]) == tg, bar);
;             __builtin_amdgcn_fence(__ATOMIC_ACQUIRE, "agent");
;             xb_add(&bar[XB_XGEN(b.x)], 1u);
;             asm volatile("s_waitcnt vmcnt(0)" ::: "memory");
;         } else {
;             XB_SPIN(xb_ld(&bar[XB_XGEN(b.x)]) == gen, bar);
.LBB0_527:
	s_lshl_b32 s4, s87, 8
	s_add_u32 s4, s88, s4
	s_addc_u32 s5, s89, 0
	v_mov_b32_e32 v1, 0x1000
	v_mov_b32_e32 v3, 1
	global_atomic_add v3, v1, v3, s[4:5] offset:1024 sc0
	buffer_inv sc1
	v_cvt_f32_u32_e32 v1, v2
	v_sub_u32_e32 v4, 0, v2
	v_rcp_iflag_f32_e32 v1, v1
	s_nop 0
	v_mul_f32_e32 v1, 0x4f7ffffe, v1
	v_cvt_u32_f32_e32 v1, v1
	v_mul_lo_u32 v4, v4, v1
	v_mul_hi_u32 v4, v1, v4
	v_add_u32_e32 v1, v1, v4
	s_waitcnt vmcnt(0)
	v_mul_hi_u32 v1, v3, v1
	v_mul_lo_u32 v4, v1, v2
	v_sub_u32_e32 v4, v3, v4
	v_add_u32_e32 v5, 1, v1
	v_cmp_ge_u32_e32 vcc, v4, v2
	v_add_u32_e32 v3, 1, v3
	s_nop 0
	v_cndmask_b32_e32 v1, v1, v5, vcc
	v_sub_u32_e32 v5, v4, v2
	v_cndmask_b32_e32 v4, v4, v5, vcc
	v_add_u32_e32 v5, 1, v1
	v_cmp_ge_u32_e32 vcc, v4, v2
	s_nop 1
	v_cndmask_b32_e32 v1, v1, v5, vcc
	v_mul_lo_u32 v4, v2, v1
	v_add_u32_e32 v2, v4, v2
	v_cmp_ne_u32_e32 vcc, v3, v2
	s_and_saveexec_b64 s[6:7], vcc
	s_xor_b64 s[6:7], exec, s[6:7]
	s_cbranch_execz .LBB0_541
	s_waitcnt lgkmcnt(0)
	v_mov_b32_e32 v0, 0x3500
	global_load_dword v0, v0, s[88:89] sc1
	s_add_u32 s12, s88, 0x3500
	s_addc_u32 s13, s89, 0
	s_waitcnt vmcnt(0)
	v_cmp_eq_u32_e32 vcc, v0, v1
	s_and_saveexec_b64 s[8:9], vcc
	s_cbranch_execz .LBB0_540
	s_add_u32 s10, s80, 0x10200
	s_addc_u32 s11, s81, 0
	s_mov_b32 s24, 1
	s_mov_b64 s[14:15], 0
	v_mov_b32_e32 v0, 0
	s_branch .LBB0_531
